# sample item wave reductions via DPP + permlane swaps (on top of bpswap + smswap)
# baseline (speedup 1.0000x reference)
.LBB0_289:
	v_lshl_add_u64 v[22:23], v[20:21], 0, s[20:21]
	v_lshl_add_u64 v[34:35], v[18:19], 0, s[20:21]
	global_load_dword v36, v[22:23], off
	global_load_dword v38, v[22:23], off offset:256
	global_load_dword v40, v[22:23], off offset:512
	global_load_dword v42, v[22:23], off offset:768
	global_load_dword v44, v[22:23], off offset:1024
	global_load_dword v46, v[22:23], off offset:1280
	global_load_dword v48, v[22:23], off offset:1536
	global_load_dword v50, v[22:23], off offset:1792
	global_load_dword v37, v[34:35], off
	global_load_dword v39, v[34:35], off offset:256
	global_load_dword v41, v[34:35], off offset:512
	global_load_dword v43, v[34:35], off offset:768
	global_load_dword v45, v[34:35], off offset:1024
	global_load_dword v47, v[34:35], off offset:1280
	global_load_dword v49, v[34:35], off offset:1536
	global_load_dword v51, v[34:35], off offset:1792
	global_load_dword v52, v[22:23], off offset:2048
	global_load_dword v54, v[22:23], off offset:2304
	global_load_dword v56, v[22:23], off offset:2560
	global_load_dword v58, v[22:23], off offset:2816
	global_load_dword v60, v[22:23], off offset:3072
	global_load_dword v62, v[22:23], off offset:3328
	global_load_dword v64, v[22:23], off offset:3584
	global_load_dword v66, v[22:23], off offset:3840
	global_load_dword v53, v[34:35], off offset:2048
	global_load_dword v55, v[34:35], off offset:2304
	global_load_dword v57, v[34:35], off offset:2560
	global_load_dword v59, v[34:35], off offset:2816
	global_load_dword v61, v[34:35], off offset:3072
	global_load_dword v63, v[34:35], off offset:3328
	global_load_dword v65, v[34:35], off offset:3584
	global_load_dword v67, v[34:35], off offset:3840
	v_add_co_u32_e32 v22, vcc, s29, v22
	v_add_u32_e32 v11, 0xffffff84, v2
	s_nop 0
	v_addc_co_u32_e32 v23, vcc, 0, v23, vcc
	v_add_co_u32_e32 v34, vcc, s29, v34
	v_add_u32_e32 v99, 0xffffff88, v2
	s_nop 0
	v_addc_co_u32_e32 v35, vcc, 0, v35, vcc
	global_load_dword v68, v[22:23], off
	global_load_dword v70, v[22:23], off offset:256
	global_load_dword v72, v[22:23], off offset:512
	global_load_dword v74, v[22:23], off offset:768
	global_load_dword v76, v[22:23], off offset:1024
	global_load_dword v78, v[22:23], off offset:1280
	global_load_dword v80, v[22:23], off offset:1536
	global_load_dword v82, v[22:23], off offset:1792
	global_load_dword v69, v[34:35], off
	global_load_dword v71, v[34:35], off offset:256
	global_load_dword v73, v[34:35], off offset:512
	global_load_dword v75, v[34:35], off offset:768
	global_load_dword v77, v[34:35], off offset:1024
	global_load_dword v79, v[34:35], off offset:1280
	global_load_dword v81, v[34:35], off offset:1536
	global_load_dword v83, v[34:35], off offset:1792
	global_load_dword v84, v[22:23], off offset:2048
	global_load_dword v86, v[22:23], off offset:2304
	global_load_dword v88, v[22:23], off offset:2560
	global_load_dword v90, v[22:23], off offset:2816
	global_load_dword v92, v[22:23], off offset:3072
	global_load_dword v94, v[22:23], off offset:3328
	global_load_dword v96, v[22:23], off offset:3584
	s_nop 0
	global_load_dword v22, v[22:23], off offset:3840
	s_nop 0
	global_load_dword v85, v[34:35], off offset:2048
	global_load_dword v87, v[34:35], off offset:2304
	global_load_dword v89, v[34:35], off offset:2560
	global_load_dword v91, v[34:35], off offset:2816
	global_load_dword v93, v[34:35], off offset:3072
	global_load_dword v95, v[34:35], off offset:3328
	global_load_dword v97, v[34:35], off offset:3584
	global_load_dword v23, v[34:35], off offset:3840
	ds_bpermute_b32 v98, v11, v1
	v_add_u32_e32 v101, 0xffffff8c, v2
	ds_bpermute_b32 v100, v99, v1
	v_add_u32_e32 v103, 0xffffff90, v2
	ds_bpermute_b32 v102, v101, v1
	v_add_u32_e32 v105, 0xffffff94, v2
	ds_bpermute_b32 v104, v103, v1
	v_add_u32_e32 v107, 0xffffff98, v2
	ds_bpermute_b32 v106, v105, v1
	v_add_u32_e32 v109, 0xffffff9c, v2
	ds_bpermute_b32 v108, v107, v1
	v_add_u32_e32 v111, 0xffffffa0, v2
	ds_bpermute_b32 v110, v109, v1
	v_add_u32_e32 v113, 0xffffffa4, v2
	ds_bpermute_b32 v112, v111, v1
	v_add_u32_e32 v115, 0xffffffa8, v2
	ds_bpermute_b32 v114, v113, v1
	v_add_u32_e32 v117, 0xffffffac, v2
	ds_bpermute_b32 v116, v115, v1
	v_add_u32_e32 v119, 0xffffffb0, v2
	ds_bpermute_b32 v118, v117, v1
	v_add_u32_e32 v121, 0xffffffb4, v2
	ds_bpermute_b32 v120, v119, v1
	v_add_u32_e32 v123, 0xffffffb8, v2
	ds_bpermute_b32 v122, v121, v1
	v_add_u32_e32 v125, 0xffffffbc, v2
	ds_bpermute_b32 v124, v123, v1
	v_subrev_u32_e32 v127, 64, v2
	ds_bpermute_b32 v126, v125, v1
	v_subrev_u32_e32 v129, 60, v2
	ds_bpermute_b32 v128, v127, v1
	v_subrev_u32_e32 v131, 56, v2
	ds_bpermute_b32 v130, v129, v1
	v_subrev_u32_e32 v133, 52, v2
	ds_bpermute_b32 v132, v131, v1
	v_subrev_u32_e32 v35, 48, v2
	ds_bpermute_b32 v134, v133, v1
	v_subrev_u32_e32 v135, 44, v2
	ds_bpermute_b32 v136, v35, v1
	v_subrev_u32_e32 v137, 40, v2
	ds_bpermute_b32 v138, v135, v1
	v_subrev_u32_e32 v139, 36, v2
	ds_bpermute_b32 v140, v137, v1
	v_subrev_u32_e32 v141, 32, v2
	ds_bpermute_b32 v142, v139, v1
	s_waitcnt vmcnt(55) lgkmcnt(14)
	v_pk_fma_f32 v[16:17], v[36:37], v[98:99], v[16:17] op_sel_hi:[1,0,1]
	v_subrev_u32_e32 v143, 28, v2
	s_waitcnt vmcnt(54)
	v_pk_fma_f32 v[16:17], v[38:39], v[100:101], v[16:17] op_sel_hi:[1,0,1]
	ds_bpermute_b32 v146, v141, v1
	s_waitcnt vmcnt(53)
	v_pk_fma_f32 v[16:17], v[40:41], v[102:103], v[16:17] op_sel_hi:[1,0,1]
	v_subrev_u32_e32 v145, 24, v2
	s_waitcnt vmcnt(52)
	v_pk_fma_f32 v[16:17], v[42:43], v[104:105], v[16:17] op_sel_hi:[1,0,1]
	ds_bpermute_b32 v148, v143, v1
	s_waitcnt vmcnt(51)
	v_pk_fma_f32 v[16:17], v[44:45], v[106:107], v[16:17] op_sel_hi:[1,0,1]
	v_subrev_u32_e32 v147, 20, v2
	s_waitcnt vmcnt(50)
	v_pk_fma_f32 v[16:17], v[46:47], v[108:109], v[16:17] op_sel_hi:[1,0,1]
	ds_bpermute_b32 v150, v145, v1
	s_waitcnt vmcnt(49)
	v_pk_fma_f32 v[16:17], v[48:49], v[110:111], v[16:17] op_sel_hi:[1,0,1]
	v_add_u32_e32 v149, -16, v2
	s_waitcnt vmcnt(48)
	v_pk_fma_f32 v[16:17], v[50:51], v[112:113], v[16:17] op_sel_hi:[1,0,1]
	ds_bpermute_b32 v152, v147, v1
	s_waitcnt vmcnt(39)
	v_pk_fma_f32 v[16:17], v[52:53], v[114:115], v[16:17] op_sel_hi:[1,0,1]
	v_add_u32_e32 v151, -12, v2
	s_waitcnt vmcnt(38) lgkmcnt(14)
	v_pk_fma_f32 v[16:17], v[54:55], v[116:117], v[16:17] op_sel_hi:[1,0,1]
	ds_bpermute_b32 v154, v149, v1
	s_waitcnt vmcnt(37)
	v_pk_fma_f32 v[16:17], v[56:57], v[118:119], v[16:17] op_sel_hi:[1,0,1]
	v_add_u32_e32 v153, -8, v2
	s_waitcnt vmcnt(36)
	v_pk_fma_f32 v[16:17], v[58:59], v[120:121], v[16:17] op_sel_hi:[1,0,1]
	ds_bpermute_b32 v156, v151, v1
	s_waitcnt vmcnt(35)
	v_pk_fma_f32 v[16:17], v[60:61], v[122:123], v[16:17] op_sel_hi:[1,0,1]
	v_add_u32_e32 v155, -4, v2
	s_waitcnt vmcnt(34) lgkmcnt(14)
	v_pk_fma_f32 v[16:17], v[62:63], v[124:125], v[16:17] op_sel_hi:[1,0,1]
	ds_bpermute_b32 v158, v153, v1
	s_waitcnt vmcnt(33)
	v_pk_fma_f32 v[16:17], v[64:65], v[126:127], v[16:17] op_sel_hi:[1,0,1]
	ds_bpermute_b32 v160, v155, v1
	s_waitcnt vmcnt(32) lgkmcnt(14)
	v_pk_fma_f32 v[16:17], v[66:67], v[128:129], v[16:17] op_sel_hi:[1,0,1]
	ds_bpermute_b32 v34, v2, v1
	s_waitcnt vmcnt(23)
	v_pk_fma_f32 v[16:17], v[68:69], v[130:131], v[16:17] op_sel_hi:[1,0,1]
	s_add_u32 s20, s20, 0x2000
	s_waitcnt vmcnt(22) lgkmcnt(14)
	v_pk_fma_f32 v[16:17], v[70:71], v[132:133], v[16:17] op_sel_hi:[1,0,1]
	s_addc_u32 s21, s21, 0
	s_waitcnt vmcnt(21) lgkmcnt(13)
	v_pk_fma_f32 v[16:17], v[72:73], v[134:135], v[16:17] op_sel_hi:[1,0,1]
	v_add_u32_e32 v2, 0x80, v2
	s_waitcnt vmcnt(20) lgkmcnt(12)
	v_pk_fma_f32 v[16:17], v[74:75], v[136:137], v[16:17] op_sel_hi:[1,0,1]
	s_cmpk_eq_i32 s20, 0x4000
	s_waitcnt vmcnt(19) lgkmcnt(11)
	v_pk_fma_f32 v[16:17], v[76:77], v[138:139], v[16:17] op_sel_hi:[1,0,1]
	s_waitcnt vmcnt(18) lgkmcnt(10)
	v_pk_fma_f32 v[16:17], v[78:79], v[140:141], v[16:17] op_sel_hi:[1,0,1]
	s_waitcnt vmcnt(17) lgkmcnt(9)
	v_pk_fma_f32 v[16:17], v[80:81], v[142:143], v[16:17] op_sel_hi:[1,0,1]
	s_waitcnt vmcnt(16) lgkmcnt(8)
	v_pk_fma_f32 v[16:17], v[82:83], v[146:147], v[16:17] op_sel_hi:[1,0,1]
	s_waitcnt vmcnt(7) lgkmcnt(7)
	v_pk_fma_f32 v[16:17], v[84:85], v[148:149], v[16:17] op_sel_hi:[1,0,1]
	s_waitcnt vmcnt(6) lgkmcnt(6)
	v_pk_fma_f32 v[16:17], v[86:87], v[150:151], v[16:17] op_sel_hi:[1,0,1]
	s_waitcnt vmcnt(5) lgkmcnt(5)
	v_pk_fma_f32 v[16:17], v[88:89], v[152:153], v[16:17] op_sel_hi:[1,0,1]
	s_waitcnt vmcnt(4) lgkmcnt(4)
	v_pk_fma_f32 v[16:17], v[90:91], v[154:155], v[16:17] op_sel_hi:[1,0,1]
	s_waitcnt vmcnt(3) lgkmcnt(3)
	v_pk_fma_f32 v[16:17], v[92:93], v[156:157], v[16:17] op_sel_hi:[1,0,1]
	s_waitcnt vmcnt(2) lgkmcnt(2)
	v_pk_fma_f32 v[16:17], v[94:95], v[158:159], v[16:17] op_sel_hi:[1,0,1]
	s_waitcnt vmcnt(1) lgkmcnt(1)
	v_pk_fma_f32 v[16:17], v[96:97], v[160:161], v[16:17] op_sel_hi:[1,0,1]
	s_waitcnt vmcnt(0) lgkmcnt(0)
	v_pk_fma_f32 v[16:17], v[22:23], v[34:35], v[16:17] op_sel_hi:[1,0,1]
	s_cbranch_scc0 .LBB0_289
	v_readlane_b32 s84, v254, 23
	v_lshlrev_b32_e32 v2, 2, v12
	v_readlane_b32 s98, v254, 37
	v_readlane_b32 s99, v254, 38
	v_mul_f32_e32 v11, 0xbfb8aa3b, v16
	v_exp_f32_e32 v11, v11
	s_lshl_b32 s51, s51, 6
	v_readlane_b32 s52, v254, 7
	s_lshr_b32 s2, s50, 2
	global_load_dword v18, v2, s[98:99]
	s_lshl_b64 s[20:21], s[18:19], 12
	s_and_b32 s51, s51, 0x300
	v_readlane_b32 s62, v254, 17
	v_readlane_b32 s53, v254, 8
	v_readlane_b32 s63, v254, 18
	s_add_u32 s52, s62, s20
	v_mul_f32_e32 v19, 0xbfb8aa3b, v17
	v_lshlrev_b32_e32 v20, 1, v0
	s_addc_u32 s53, s63, s21
	v_add_f32_e32 v11, 1.0, v11
	v_exp_f32_e32 v21, v19
	v_lshl_or_b32 v19, s2, 7, v20
	global_load_dword v20, v2, s[52:53]
	v_rcp_f32_e32 v22, v11
	v_add_co_u32_e32 v16, vcc, s29, v14
	v_add_f32_e32 v21, 1.0, v21
	s_nop 0
	v_addc_co_u32_e32 v17, vcc, 0, v15, vcc
	v_mul_f32_e32 v22, 0xc1000000, v22
	v_rcp_f32_e32 v21, v21
	s_add_u32 s20, s80, s20
	s_addc_u32 s21, s81, s21
	s_lshl_b32 s18, s18, 7
	v_readlane_b32 s56, v254, 11
	v_readlane_b32 s57, v254, 12
	s_lshl_b32 s2, s2, 8
	v_mov_b32_e32 v126, s24
	v_readlane_b32 s85, v254, 24
	s_ashr_i32 s19, s18, 31
	v_readlane_b32 s86, v254, 25
	v_readlane_b32 s87, v254, 26
	v_readlane_b32 s88, v254, 27
	v_readlane_b32 s89, v254, 28
	v_readlane_b32 s90, v254, 29
	v_readlane_b32 s91, v254, 30
	v_readlane_b32 s92, v254, 31
	v_readlane_b32 s93, v254, 32
	v_readlane_b32 s94, v254, 33
	v_readlane_b32 s95, v254, 34
	v_readlane_b32 s96, v254, 35
	v_readlane_b32 s97, v254, 36
	v_readlane_b32 s54, v254, 9
	v_readlane_b32 s55, v254, 10
	v_readlane_b32 s58, v254, 13
	v_readlane_b32 s59, v254, 14
	v_readlane_b32 s60, v254, 15
	v_readlane_b32 s61, v254, 16
	v_readlane_b32 s64, v254, 19
	v_readlane_b32 s65, v254, 20
	v_readlane_b32 s66, v254, 21
	v_readlane_b32 s67, v254, 22
	s_waitcnt vmcnt(1)
	v_mul_f32_e32 v11, 0xbfb8aa3b, v18
	v_fma_f32 v23, v18, s33, -v11
	v_rndne_f32_e32 v34, v11
	v_fmac_f32_e32 v23, 0xb2a5705f, v18
	v_sub_f32_e32 v11, v11, v34
	v_add_f32_e32 v11, v11, v23
	v_cvt_i32_f32_e32 v34, v34
	v_exp_f32_e32 v23, v11
	global_load_ushort v11, v[16:17], off offset:1024
	global_load_ushort v35, v19, s[0:1] offset:2560
	global_load_ushort v80, v19, s[0:1] offset:2048
	global_load_ushort v36, v[14:15], off
	v_cmp_nlt_f32_e32 vcc, s34, v18
	v_ldexp_f32 v19, v23, v34
	s_nop 0
	v_cndmask_b32_e32 v19, 0, v19, vcc
	v_cmp_ngt_f32_e32 vcc, s35, v18
	s_nop 1
	v_cndmask_b32_e32 v23, v33, v19, vcc
	v_add_f32_e32 v34, 1.0, v23
	v_add_f32_e32 v37, -1.0, v34
	v_frexp_mant_f32_e32 v38, v34
	v_cvt_f64_f32_e32 v[18:19], v34
	v_sub_f32_e32 v39, v37, v34
	v_frexp_exp_i32_f64_e32 v18, v[18:19]
	v_cmp_gt_f32_e32 vcc, s37, v38
	v_sub_f32_e32 v37, v23, v37
	v_add_f32_e32 v19, 1.0, v39
	v_subbrev_co_u32_e32 v18, vcc, 0, v18, vcc
	v_add_f32_e32 v19, v37, v19
	v_sub_u32_e32 v37, 0, v18
	v_cvt_f32_i32_e32 v18, v18
	v_ldexp_f32 v34, v34, v37
	v_ldexp_f32 v19, v19, v37
	v_add_f32_e32 v37, -1.0, v34
	v_add_f32_e32 v38, 1.0, v34
	v_add_f32_e32 v39, 1.0, v37
	v_add_f32_e32 v40, -1.0, v38
	v_sub_f32_e32 v39, v34, v39
	v_sub_f32_e32 v34, v34, v40
	v_mul_f32_e32 v40, 0x3f317218, v18
	v_add_f32_e32 v39, v19, v39
	v_add_f32_e32 v19, v19, v34
	v_fma_f32 v34, v18, s38, -v40
	v_add_f32_e32 v41, v37, v39
	v_add_f32_e32 v42, v38, v19
	v_fmac_f32_e32 v34, 0xb102e308, v18
	v_sub_f32_e32 v18, v37, v41
	v_sub_f32_e32 v37, v38, v42
	v_rcp_f32_e32 v38, v42
	v_add_f32_e32 v43, v40, v34
	v_add_f32_e32 v19, v19, v37
	v_sub_f32_e32 v37, v43, v40
	v_sub_f32_e32 v34, v34, v37
	v_mul_f32_e32 v37, v41, v38
	v_add_f32_e32 v18, v39, v18
	v_mul_f32_e32 v39, v42, v37
	v_fma_f32 v40, v37, v42, -v39
	v_fmac_f32_e32 v40, v37, v19
	v_add_f32_e32 v44, v39, v40
	v_sub_f32_e32 v45, v41, v44
	v_sub_f32_e32 v39, v44, v39
	v_sub_f32_e32 v41, v41, v45
	v_sub_f32_e32 v39, v39, v40
	v_sub_f32_e32 v40, v41, v44
	v_add_f32_e32 v18, v18, v40
	v_add_f32_e32 v18, v39, v18
	v_add_f32_e32 v39, v45, v18
	v_mul_f32_e32 v40, v38, v39
	v_sub_f32_e32 v41, v45, v39
	v_mul_f32_e32 v44, v42, v40
	v_add_f32_e32 v18, v18, v41
	v_add_f32_e32 v41, v37, v40
	v_fma_f32 v42, v40, v42, -v44
	v_sub_f32_e32 v37, v41, v37
	v_fmac_f32_e32 v42, v40, v19
	v_sub_f32_e32 v19, v40, v37
	v_add_f32_e32 v37, v44, v42
	v_sub_f32_e32 v40, v37, v44
	v_sub_f32_e32 v44, v39, v37
	v_sub_f32_e32 v39, v39, v44
	v_sub_f32_e32 v37, v39, v37
	v_sub_f32_e32 v40, v40, v42
	v_add_f32_e32 v18, v18, v37
	v_add_f32_e32 v18, v40, v18
	v_add_f32_e32 v18, v44, v18
	v_mul_f32_e32 v18, v38, v18
	v_add_f32_e32 v18, v19, v18
	v_add_f32_e32 v19, v41, v18
	v_mul_f32_e32 v37, v19, v19
	v_fmamk_f32 v40, v37, 0x3e9b6dac, v31
	v_sub_f32_e32 v38, v19, v41
	v_ldexp_f32 v39, v19, 1
	v_mul_f32_e32 v19, v19, v37
	v_fmaak_f32 v37, v37, v40, 0x3f2aaada
	v_mul_f32_e32 v19, v19, v37
	v_add_f32_e32 v37, v39, v19
	v_sub_f32_e32 v18, v18, v38
	v_sub_f32_e32 v38, v37, v39
	v_ldexp_f32 v18, v18, 1
	v_sub_f32_e32 v19, v19, v38
	v_add_f32_e32 v18, v18, v19
	v_add_f32_e32 v19, v37, v18
	v_sub_f32_e32 v37, v19, v37
	v_add_f32_e32 v38, v43, v19
	v_sub_f32_e32 v18, v18, v37
	v_sub_f32_e32 v37, v38, v43
	v_sub_f32_e32 v39, v38, v37
	v_sub_f32_e32 v19, v19, v37
	v_add_f32_e32 v37, v34, v18
	v_sub_f32_e32 v39, v43, v39
	v_sub_f32_e32 v40, v37, v34
	v_add_f32_e32 v19, v19, v39
	v_sub_f32_e32 v39, v37, v40
	v_sub_f32_e32 v18, v18, v40
	v_sub_f32_e32 v34, v34, v39
	v_add_f32_e32 v19, v37, v19
	v_add_f32_e32 v18, v18, v34
	v_add_f32_e32 v34, v38, v19
	v_sub_f32_e32 v37, v34, v38
	v_sub_f32_e32 v19, v19, v37
	v_add_f32_e32 v18, v18, v19
	v_add_f32_e32 v18, v34, v18
	v_cmp_neq_f32_e32 vcc, s36, v23
	s_nop 1
	v_cndmask_b32_e32 v18, v33, v18, vcc
	v_cmp_lt_f32_e64 vcc, |v23|, s39
	s_nop 1
	v_cndmask_b32_e32 v18, v18, v23, vcc
	v_mul_f32_e32 v18, v22, v18
	v_add_f32_e32 v19, v18, v18
	v_mul_f32_e32 v19, 0x3fb8aa3b, v19
	v_exp_f32_e32 v19, v19
	v_mul_f32_e32 v18, 0x3fb8aa3b, v18
	v_exp_f32_e32 v18, v18
	v_sub_f32_e32 v19, 1.0, v19
	v_max_f32_e32 v19, 0, v19
	v_mul_f32_e32 v22, 0x4f800000, v19
	v_cmp_gt_f32_e32 vcc, s40, v19
	s_nop 1
	v_cndmask_b32_e32 v19, v19, v22, vcc
	v_sqrt_f32_e32 v22, v19
	s_nop 0
	v_add_u32_e32 v23, -1, v22
	v_add_u32_e32 v34, 1, v22
	v_fma_f32 v37, -v23, v22, v19
	v_fma_f32 v38, -v34, v22, v19
	v_cmp_ge_f32_e64 s[0:1], 0, v37
	s_nop 1
	v_cndmask_b32_e64 v22, v22, v23, s[0:1]
	v_cmp_lt_f32_e64 s[0:1], 0, v38
	s_nop 1
	v_cndmask_b32_e64 v22, v22, v34, s[0:1]
	v_mul_f32_e32 v23, 0x37800000, v22
	v_cndmask_b32_e32 v22, v22, v23, vcc
	v_cmp_class_f32_e32 vcc, v19, v32
	s_lshl_b32 s0, s50, 2
	s_nop 0
	v_cndmask_b32_e32 v19, v22, v19, vcc
	v_mul_f32_e32 v19, v21, v19
	v_mul_f32_e32 v34, v1, v19
	s_waitcnt vmcnt(4)
	v_fmac_f32_e32 v34, v20, v18
	v_lshl_add_u64 v[18:19], s[20:21], 0, v[2:3]
	v_add_co_u32_e32 v18, vcc, s41, v18
	s_waitcnt vmcnt(0)
	v_lshlrev_b32_e32 v2, 16, v36
	v_addc_co_u32_e32 v19, vcc, 0, v19, vcc
	global_store_dword v[18:19], v34, off
	v_or_b32_e32 v18, s18, v0
	v_ashrrev_i32_e32 v19, 31, v18
	v_lshlrev_b64 v[18:19], 10, v[18:19]
	v_lshl_add_u64 v[18:19], s[56:57], 0, v[18:19]
	v_lshl_add_u64 v[18:19], v[18:19], 0, s[2:3]
	ds_write_b32 v13, v2
	s_waitcnt lgkmcnt(0)
	v_lshlrev_b32_e32 v1, 16, v80
	v_and_b32_e32 v21, 15, v0
	v_lshrrev_b32_e32 v22, 4, v0
	v_lshl_add_u32 v113, v22, 2, v126
	v_lshlrev_b32_e32 v23, 4, v22
	v_sub_u32_e32 v23, v23, v22
	v_add_u32_e32 v23, v23, v21
	v_lshlrev_b32_e32 v23, 10, v23
	v_lshlrev_b32_e32 v112, 4, v21
	v_sub_u32_e32 v22, v112, v23
	v_add_u32_e32 v22, 0x1000, v22
	v_add_u32_e32 v112, v126, v112
	v_ashrrev_i32_e32 v23, 31, v22
	ds_read_b128 v[116:119], v112
	v_mov_b32_e32 v114, 0x2000
	v_mov_b32_e32 v115, 0
	v_lshl_add_u64 v[22:23], v[18:19], 0, v[22:23]
	global_load_dwordx4 v[36:39], v[22:23], off offset:-4096
	global_load_dwordx4 v[40:43], v[22:23], off
	v_lshl_add_u64 v[22:23], v[22:23], 0, v[114:115]
	global_load_dwordx4 v[44:47], v[22:23], off offset:-4096
	global_load_dwordx4 v[48:51], v[22:23], off
	v_lshl_add_u64 v[22:23], v[22:23], 0, v[114:115]
	global_load_dwordx4 v[52:55], v[22:23], off offset:-4096
	global_load_dwordx4 v[56:59], v[22:23], off
	v_lshl_add_u64 v[22:23], v[22:23], 0, v[114:115]
	global_load_dwordx4 v[60:63], v[22:23], off offset:-4096
	global_load_dwordx4 v[64:67], v[22:23], off
	v_lshl_add_u64 v[22:23], v[22:23], 0, v[114:115]
	global_load_dwordx4 v[68:71], v[22:23], off offset:-4096
	global_load_dwordx4 v[72:75], v[22:23], off
	v_lshl_add_u64 v[22:23], v[22:23], 0, v[114:115]
	global_load_dwordx4 v[76:79], v[22:23], off offset:-4096
	global_load_dwordx4 v[80:83], v[22:23], off
	v_lshl_add_u64 v[22:23], v[22:23], 0, v[114:115]
	global_load_dwordx4 v[84:87], v[22:23], off offset:-4096
	global_load_dwordx4 v[88:91], v[22:23], off
	v_lshl_add_u64 v[22:23], v[22:23], 0, v[114:115]
	global_load_dwordx4 v[92:95], v[22:23], off offset:-4096
	global_load_dwordx4 v[96:99], v[22:23], off
	v_lshl_add_u64 v[22:23], v[22:23], 0, v[114:115]
	s_waitcnt vmcnt(12) lgkmcnt(0)
	v_mul_f32_e32 v100, v36, v116
	v_mul_f32_e32 v101, v40, v116
	v_mul_f32_e32 v102, v44, v116
	v_mul_f32_e32 v103, v48, v116
	v_fmac_f32_e32 v100, v37, v117
	v_fmac_f32_e32 v101, v41, v117
	v_fmac_f32_e32 v102, v45, v117
	v_fmac_f32_e32 v103, v49, v117
	v_fmac_f32_e32 v100, v38, v118
	v_fmac_f32_e32 v101, v42, v118
	v_fmac_f32_e32 v102, v46, v118
	v_fmac_f32_e32 v103, v50, v118
	v_fmac_f32_e32 v100, v39, v119
	v_fmac_f32_e32 v101, v43, v119
	v_fmac_f32_e32 v102, v47, v119
	v_fmac_f32_e32 v103, v51, v119
	global_load_dwordx4 v[36:39], v[22:23], off offset:-4096
	global_load_dwordx4 v[40:43], v[22:23], off
	v_lshl_add_u64 v[22:23], v[22:23], 0, v[114:115]
	global_load_dwordx4 v[44:47], v[22:23], off offset:-4096
	global_load_dwordx4 v[48:51], v[22:23], off
	v_lshl_add_u64 v[22:23], v[22:23], 0, v[114:115]
	v_add_f32_dpp v100, v100, v100 row_ror:8 row_mask:0xf bank_mask:0xf
	v_add_f32_dpp v101, v101, v101 row_ror:8 row_mask:0xf bank_mask:0xf
	v_add_f32_dpp v102, v102, v102 row_ror:8 row_mask:0xf bank_mask:0xf
	v_add_f32_dpp v103, v103, v103 row_ror:8 row_mask:0xf bank_mask:0xf
	v_add_f32_dpp v100, v100, v100 row_ror:4 row_mask:0xf bank_mask:0xf
	v_add_f32_dpp v101, v101, v101 row_ror:4 row_mask:0xf bank_mask:0xf
	v_add_f32_dpp v102, v102, v102 row_ror:4 row_mask:0xf bank_mask:0xf
	v_add_f32_dpp v103, v103, v103 row_ror:4 row_mask:0xf bank_mask:0xf
	v_add_f32_dpp v100, v100, v100 row_ror:2 row_mask:0xf bank_mask:0xf
	v_add_f32_dpp v101, v101, v101 row_ror:2 row_mask:0xf bank_mask:0xf
	v_add_f32_dpp v102, v102, v102 row_ror:2 row_mask:0xf bank_mask:0xf
	v_add_f32_dpp v103, v103, v103 row_ror:2 row_mask:0xf bank_mask:0xf
	v_add_f32_dpp v100, v100, v100 row_ror:1 row_mask:0xf bank_mask:0xf
	v_add_f32_dpp v101, v101, v101 row_ror:1 row_mask:0xf bank_mask:0xf
	v_add_f32_dpp v102, v102, v102 row_ror:1 row_mask:0xf bank_mask:0xf
	v_add_f32_dpp v103, v103, v103 row_ror:1 row_mask:0xf bank_mask:0xf
	s_nop 1
	ds_write_b32 v113, v100 offset:256
	ds_write_b32 v113, v101 offset:272
	ds_write_b32 v113, v102 offset:288
	ds_write_b32 v113, v103 offset:304
	s_waitcnt vmcnt(12)
	v_mul_f32_e32 v104, v52, v116
	v_mul_f32_e32 v105, v56, v116
	v_mul_f32_e32 v106, v60, v116
	v_mul_f32_e32 v107, v64, v116
	v_fmac_f32_e32 v104, v53, v117
	v_fmac_f32_e32 v105, v57, v117
	v_fmac_f32_e32 v106, v61, v117
	v_fmac_f32_e32 v107, v65, v117
	v_fmac_f32_e32 v104, v54, v118
	v_fmac_f32_e32 v105, v58, v118
	v_fmac_f32_e32 v106, v62, v118
	v_fmac_f32_e32 v107, v66, v118
	v_fmac_f32_e32 v104, v55, v119
	v_fmac_f32_e32 v105, v59, v119
	v_fmac_f32_e32 v106, v63, v119
	v_fmac_f32_e32 v107, v67, v119
	global_load_dwordx4 v[52:55], v[22:23], off offset:-4096
	global_load_dwordx4 v[56:59], v[22:23], off
	v_lshl_add_u64 v[22:23], v[22:23], 0, v[114:115]
	global_load_dwordx4 v[60:63], v[22:23], off offset:-4096
	global_load_dwordx4 v[64:67], v[22:23], off
	v_lshl_add_u64 v[22:23], v[22:23], 0, v[114:115]
	v_add_f32_dpp v104, v104, v104 row_ror:8 row_mask:0xf bank_mask:0xf
	v_add_f32_dpp v105, v105, v105 row_ror:8 row_mask:0xf bank_mask:0xf
	v_add_f32_dpp v106, v106, v106 row_ror:8 row_mask:0xf bank_mask:0xf
	v_add_f32_dpp v107, v107, v107 row_ror:8 row_mask:0xf bank_mask:0xf
	v_add_f32_dpp v104, v104, v104 row_ror:4 row_mask:0xf bank_mask:0xf
	v_add_f32_dpp v105, v105, v105 row_ror:4 row_mask:0xf bank_mask:0xf
	v_add_f32_dpp v106, v106, v106 row_ror:4 row_mask:0xf bank_mask:0xf
	v_add_f32_dpp v107, v107, v107 row_ror:4 row_mask:0xf bank_mask:0xf
	v_add_f32_dpp v104, v104, v104 row_ror:2 row_mask:0xf bank_mask:0xf
	v_add_f32_dpp v105, v105, v105 row_ror:2 row_mask:0xf bank_mask:0xf
	v_add_f32_dpp v106, v106, v106 row_ror:2 row_mask:0xf bank_mask:0xf
	v_add_f32_dpp v107, v107, v107 row_ror:2 row_mask:0xf bank_mask:0xf
	v_add_f32_dpp v104, v104, v104 row_ror:1 row_mask:0xf bank_mask:0xf
	v_add_f32_dpp v105, v105, v105 row_ror:1 row_mask:0xf bank_mask:0xf
	v_add_f32_dpp v106, v106, v106 row_ror:1 row_mask:0xf bank_mask:0xf
	v_add_f32_dpp v107, v107, v107 row_ror:1 row_mask:0xf bank_mask:0xf
	s_nop 1
	ds_write_b32 v113, v104 offset:320
	ds_write_b32 v113, v105 offset:336
	ds_write_b32 v113, v106 offset:352
	ds_write_b32 v113, v107 offset:368
	s_waitcnt vmcnt(12)
	v_mul_f32_e32 v100, v68, v116
	v_mul_f32_e32 v101, v72, v116
	v_mul_f32_e32 v102, v76, v116
	v_mul_f32_e32 v103, v80, v116
	v_fmac_f32_e32 v100, v69, v117
	v_fmac_f32_e32 v101, v73, v117
	v_fmac_f32_e32 v102, v77, v117
	v_fmac_f32_e32 v103, v81, v117
	v_fmac_f32_e32 v100, v70, v118
	v_fmac_f32_e32 v101, v74, v118
	v_fmac_f32_e32 v102, v78, v118
	v_fmac_f32_e32 v103, v82, v118
	v_fmac_f32_e32 v100, v71, v119
	v_fmac_f32_e32 v101, v75, v119
	v_fmac_f32_e32 v102, v79, v119
	v_fmac_f32_e32 v103, v83, v119
	global_load_dwordx4 v[68:71], v[22:23], off offset:-4096
	global_load_dwordx4 v[72:75], v[22:23], off
	v_lshl_add_u64 v[22:23], v[22:23], 0, v[114:115]
	global_load_dwordx4 v[76:79], v[22:23], off offset:-4096
	global_load_dwordx4 v[80:83], v[22:23], off
	v_lshl_add_u64 v[22:23], v[22:23], 0, v[114:115]
	v_add_f32_dpp v100, v100, v100 row_ror:8 row_mask:0xf bank_mask:0xf
	v_add_f32_dpp v101, v101, v101 row_ror:8 row_mask:0xf bank_mask:0xf
	v_add_f32_dpp v102, v102, v102 row_ror:8 row_mask:0xf bank_mask:0xf
	v_add_f32_dpp v103, v103, v103 row_ror:8 row_mask:0xf bank_mask:0xf
	v_add_f32_dpp v100, v100, v100 row_ror:4 row_mask:0xf bank_mask:0xf
	v_add_f32_dpp v101, v101, v101 row_ror:4 row_mask:0xf bank_mask:0xf
	v_add_f32_dpp v102, v102, v102 row_ror:4 row_mask:0xf bank_mask:0xf
	v_add_f32_dpp v103, v103, v103 row_ror:4 row_mask:0xf bank_mask:0xf
	v_add_f32_dpp v100, v100, v100 row_ror:2 row_mask:0xf bank_mask:0xf
	v_add_f32_dpp v101, v101, v101 row_ror:2 row_mask:0xf bank_mask:0xf
	v_add_f32_dpp v102, v102, v102 row_ror:2 row_mask:0xf bank_mask:0xf
	v_add_f32_dpp v103, v103, v103 row_ror:2 row_mask:0xf bank_mask:0xf
	v_add_f32_dpp v100, v100, v100 row_ror:1 row_mask:0xf bank_mask:0xf
	v_add_f32_dpp v101, v101, v101 row_ror:1 row_mask:0xf bank_mask:0xf
	v_add_f32_dpp v102, v102, v102 row_ror:1 row_mask:0xf bank_mask:0xf
	v_add_f32_dpp v103, v103, v103 row_ror:1 row_mask:0xf bank_mask:0xf
	s_nop 1
	ds_write_b32 v113, v100 offset:384
	ds_write_b32 v113, v101 offset:400
	ds_write_b32 v113, v102 offset:416
	ds_write_b32 v113, v103 offset:432
	s_waitcnt vmcnt(12)
	v_mul_f32_e32 v104, v84, v116
	v_mul_f32_e32 v105, v88, v116
	v_mul_f32_e32 v106, v92, v116
	v_mul_f32_e32 v107, v96, v116
	v_fmac_f32_e32 v104, v85, v117
	v_fmac_f32_e32 v105, v89, v117
	v_fmac_f32_e32 v106, v93, v117
	v_fmac_f32_e32 v107, v97, v117
	v_fmac_f32_e32 v104, v86, v118
	v_fmac_f32_e32 v105, v90, v118
	v_fmac_f32_e32 v106, v94, v118
	v_fmac_f32_e32 v107, v98, v118
	v_fmac_f32_e32 v104, v87, v119
	v_fmac_f32_e32 v105, v91, v119
	v_fmac_f32_e32 v106, v95, v119
	v_fmac_f32_e32 v107, v99, v119
	global_load_dwordx4 v[84:87], v[22:23], off offset:-4096
	global_load_dwordx4 v[88:91], v[22:23], off
	v_lshl_add_u64 v[22:23], v[22:23], 0, v[114:115]
	global_load_dwordx4 v[92:95], v[22:23], off offset:-4096
	global_load_dwordx4 v[96:99], v[22:23], off
	v_mov_b32_e32 v20, s0
	global_load_dword v20, v20, s[84:85]
	v_add_f32_dpp v104, v104, v104 row_ror:8 row_mask:0xf bank_mask:0xf
	v_add_f32_dpp v105, v105, v105 row_ror:8 row_mask:0xf bank_mask:0xf
	v_add_f32_dpp v106, v106, v106 row_ror:8 row_mask:0xf bank_mask:0xf
	v_add_f32_dpp v107, v107, v107 row_ror:8 row_mask:0xf bank_mask:0xf
	v_add_f32_dpp v104, v104, v104 row_ror:4 row_mask:0xf bank_mask:0xf
	v_add_f32_dpp v105, v105, v105 row_ror:4 row_mask:0xf bank_mask:0xf
	v_add_f32_dpp v106, v106, v106 row_ror:4 row_mask:0xf bank_mask:0xf
	v_add_f32_dpp v107, v107, v107 row_ror:4 row_mask:0xf bank_mask:0xf
	v_add_f32_dpp v104, v104, v104 row_ror:2 row_mask:0xf bank_mask:0xf
	v_add_f32_dpp v105, v105, v105 row_ror:2 row_mask:0xf bank_mask:0xf
	v_add_f32_dpp v106, v106, v106 row_ror:2 row_mask:0xf bank_mask:0xf
	v_add_f32_dpp v107, v107, v107 row_ror:2 row_mask:0xf bank_mask:0xf
	v_add_f32_dpp v104, v104, v104 row_ror:1 row_mask:0xf bank_mask:0xf
	v_add_f32_dpp v105, v105, v105 row_ror:1 row_mask:0xf bank_mask:0xf
	v_add_f32_dpp v106, v106, v106 row_ror:1 row_mask:0xf bank_mask:0xf
	v_add_f32_dpp v107, v107, v107 row_ror:1 row_mask:0xf bank_mask:0xf
	s_nop 1
	ds_write_b32 v113, v104 offset:448
	ds_write_b32 v113, v105 offset:464
	ds_write_b32 v113, v106 offset:480
	ds_write_b32 v113, v107 offset:496
	s_waitcnt vmcnt(13)
	v_mul_f32_e32 v100, v36, v116
	v_mul_f32_e32 v101, v40, v116
	v_mul_f32_e32 v102, v44, v116
	v_mul_f32_e32 v103, v48, v116
	v_fmac_f32_e32 v100, v37, v117
	v_fmac_f32_e32 v101, v41, v117
	v_fmac_f32_e32 v102, v45, v117
	v_fmac_f32_e32 v103, v49, v117
	v_fmac_f32_e32 v100, v38, v118
	v_fmac_f32_e32 v101, v42, v118
	v_fmac_f32_e32 v102, v46, v118
	v_fmac_f32_e32 v103, v50, v118
	v_fmac_f32_e32 v100, v39, v119
	v_fmac_f32_e32 v101, v43, v119
	v_fmac_f32_e32 v102, v47, v119
	v_fmac_f32_e32 v103, v51, v119
	v_add_f32_dpp v100, v100, v100 row_ror:8 row_mask:0xf bank_mask:0xf
	v_add_f32_dpp v101, v101, v101 row_ror:8 row_mask:0xf bank_mask:0xf
	v_add_f32_dpp v102, v102, v102 row_ror:8 row_mask:0xf bank_mask:0xf
	v_add_f32_dpp v103, v103, v103 row_ror:8 row_mask:0xf bank_mask:0xf
	v_add_f32_dpp v100, v100, v100 row_ror:4 row_mask:0xf bank_mask:0xf
	v_add_f32_dpp v101, v101, v101 row_ror:4 row_mask:0xf bank_mask:0xf
	v_add_f32_dpp v102, v102, v102 row_ror:4 row_mask:0xf bank_mask:0xf
	v_add_f32_dpp v103, v103, v103 row_ror:4 row_mask:0xf bank_mask:0xf
	v_add_f32_dpp v100, v100, v100 row_ror:2 row_mask:0xf bank_mask:0xf
	v_add_f32_dpp v101, v101, v101 row_ror:2 row_mask:0xf bank_mask:0xf
	v_add_f32_dpp v102, v102, v102 row_ror:2 row_mask:0xf bank_mask:0xf
	v_add_f32_dpp v103, v103, v103 row_ror:2 row_mask:0xf bank_mask:0xf
	v_add_f32_dpp v100, v100, v100 row_ror:1 row_mask:0xf bank_mask:0xf
	v_add_f32_dpp v101, v101, v101 row_ror:1 row_mask:0xf bank_mask:0xf
	v_add_f32_dpp v102, v102, v102 row_ror:1 row_mask:0xf bank_mask:0xf
	v_add_f32_dpp v103, v103, v103 row_ror:1 row_mask:0xf bank_mask:0xf
	s_nop 1
	ds_write_b32 v113, v100 offset:512
	ds_write_b32 v113, v101 offset:528
	ds_write_b32 v113, v102 offset:544
	ds_write_b32 v113, v103 offset:560
	s_waitcnt vmcnt(9)
	v_mul_f32_e32 v104, v52, v116
	v_mul_f32_e32 v105, v56, v116
	v_mul_f32_e32 v106, v60, v116
	v_mul_f32_e32 v107, v64, v116
	v_fmac_f32_e32 v104, v53, v117
	v_fmac_f32_e32 v105, v57, v117
	v_fmac_f32_e32 v106, v61, v117
	v_fmac_f32_e32 v107, v65, v117
	v_fmac_f32_e32 v104, v54, v118
	v_fmac_f32_e32 v105, v58, v118
	v_fmac_f32_e32 v106, v62, v118
	v_fmac_f32_e32 v107, v66, v118
	v_fmac_f32_e32 v104, v55, v119
	v_fmac_f32_e32 v105, v59, v119
	v_fmac_f32_e32 v106, v63, v119
	v_fmac_f32_e32 v107, v67, v119
	v_add_f32_dpp v104, v104, v104 row_ror:8 row_mask:0xf bank_mask:0xf
	v_add_f32_dpp v105, v105, v105 row_ror:8 row_mask:0xf bank_mask:0xf
	v_add_f32_dpp v106, v106, v106 row_ror:8 row_mask:0xf bank_mask:0xf
	v_add_f32_dpp v107, v107, v107 row_ror:8 row_mask:0xf bank_mask:0xf
	v_add_f32_dpp v104, v104, v104 row_ror:4 row_mask:0xf bank_mask:0xf
	v_add_f32_dpp v105, v105, v105 row_ror:4 row_mask:0xf bank_mask:0xf
	v_add_f32_dpp v106, v106, v106 row_ror:4 row_mask:0xf bank_mask:0xf
	v_add_f32_dpp v107, v107, v107 row_ror:4 row_mask:0xf bank_mask:0xf
	v_add_f32_dpp v104, v104, v104 row_ror:2 row_mask:0xf bank_mask:0xf
	v_add_f32_dpp v105, v105, v105 row_ror:2 row_mask:0xf bank_mask:0xf
	v_add_f32_dpp v106, v106, v106 row_ror:2 row_mask:0xf bank_mask:0xf
	v_add_f32_dpp v107, v107, v107 row_ror:2 row_mask:0xf bank_mask:0xf
	v_add_f32_dpp v104, v104, v104 row_ror:1 row_mask:0xf bank_mask:0xf
	v_add_f32_dpp v105, v105, v105 row_ror:1 row_mask:0xf bank_mask:0xf
	v_add_f32_dpp v106, v106, v106 row_ror:1 row_mask:0xf bank_mask:0xf
	v_add_f32_dpp v107, v107, v107 row_ror:1 row_mask:0xf bank_mask:0xf
	s_nop 1
	ds_write_b32 v113, v104 offset:576
	ds_write_b32 v113, v105 offset:592
	ds_write_b32 v113, v106 offset:608
	ds_write_b32 v113, v107 offset:624
	s_waitcnt vmcnt(5)
	v_mul_f32_e32 v100, v68, v116
	v_mul_f32_e32 v101, v72, v116
	v_mul_f32_e32 v102, v76, v116
	v_mul_f32_e32 v103, v80, v116
	v_fmac_f32_e32 v100, v69, v117
	v_fmac_f32_e32 v101, v73, v117
	v_fmac_f32_e32 v102, v77, v117
	v_fmac_f32_e32 v103, v81, v117
	v_fmac_f32_e32 v100, v70, v118
	v_fmac_f32_e32 v101, v74, v118
	v_fmac_f32_e32 v102, v78, v118
	v_fmac_f32_e32 v103, v82, v118
	v_fmac_f32_e32 v100, v71, v119
	v_fmac_f32_e32 v101, v75, v119
	v_fmac_f32_e32 v102, v79, v119
	v_fmac_f32_e32 v103, v83, v119
	v_add_f32_dpp v100, v100, v100 row_ror:8 row_mask:0xf bank_mask:0xf
	v_add_f32_dpp v101, v101, v101 row_ror:8 row_mask:0xf bank_mask:0xf
	v_add_f32_dpp v102, v102, v102 row_ror:8 row_mask:0xf bank_mask:0xf
	v_add_f32_dpp v103, v103, v103 row_ror:8 row_mask:0xf bank_mask:0xf
	v_add_f32_dpp v100, v100, v100 row_ror:4 row_mask:0xf bank_mask:0xf
	v_add_f32_dpp v101, v101, v101 row_ror:4 row_mask:0xf bank_mask:0xf
	v_add_f32_dpp v102, v102, v102 row_ror:4 row_mask:0xf bank_mask:0xf
	v_add_f32_dpp v103, v103, v103 row_ror:4 row_mask:0xf bank_mask:0xf
	v_add_f32_dpp v100, v100, v100 row_ror:2 row_mask:0xf bank_mask:0xf
	v_add_f32_dpp v101, v101, v101 row_ror:2 row_mask:0xf bank_mask:0xf
	v_add_f32_dpp v102, v102, v102 row_ror:2 row_mask:0xf bank_mask:0xf
	v_add_f32_dpp v103, v103, v103 row_ror:2 row_mask:0xf bank_mask:0xf
	v_add_f32_dpp v100, v100, v100 row_ror:1 row_mask:0xf bank_mask:0xf
	v_add_f32_dpp v101, v101, v101 row_ror:1 row_mask:0xf bank_mask:0xf
	v_add_f32_dpp v102, v102, v102 row_ror:1 row_mask:0xf bank_mask:0xf
	v_add_f32_dpp v103, v103, v103 row_ror:1 row_mask:0xf bank_mask:0xf
	s_nop 1
	ds_write_b32 v113, v100 offset:640
	ds_write_b32 v113, v101 offset:656
	ds_write_b32 v113, v102 offset:672
	ds_write_b32 v113, v103 offset:688
	s_waitcnt vmcnt(1)
	v_mul_f32_e32 v104, v84, v116
	v_mul_f32_e32 v105, v88, v116
	v_mul_f32_e32 v106, v92, v116
	v_mul_f32_e32 v107, v96, v116
	v_fmac_f32_e32 v104, v85, v117
	v_fmac_f32_e32 v105, v89, v117
	v_fmac_f32_e32 v106, v93, v117
	v_fmac_f32_e32 v107, v97, v117
	v_fmac_f32_e32 v104, v86, v118
	v_fmac_f32_e32 v105, v90, v118
	v_fmac_f32_e32 v106, v94, v118
	v_fmac_f32_e32 v107, v98, v118
	v_fmac_f32_e32 v104, v87, v119
	v_fmac_f32_e32 v105, v91, v119
	v_fmac_f32_e32 v106, v95, v119
	v_fmac_f32_e32 v107, v99, v119
	v_add_f32_dpp v104, v104, v104 row_ror:8 row_mask:0xf bank_mask:0xf
	v_add_f32_dpp v105, v105, v105 row_ror:8 row_mask:0xf bank_mask:0xf
	v_add_f32_dpp v106, v106, v106 row_ror:8 row_mask:0xf bank_mask:0xf
	v_add_f32_dpp v107, v107, v107 row_ror:8 row_mask:0xf bank_mask:0xf
	v_add_f32_dpp v104, v104, v104 row_ror:4 row_mask:0xf bank_mask:0xf
	v_add_f32_dpp v105, v105, v105 row_ror:4 row_mask:0xf bank_mask:0xf
	v_add_f32_dpp v106, v106, v106 row_ror:4 row_mask:0xf bank_mask:0xf
	v_add_f32_dpp v107, v107, v107 row_ror:4 row_mask:0xf bank_mask:0xf
	v_add_f32_dpp v104, v104, v104 row_ror:2 row_mask:0xf bank_mask:0xf
	v_add_f32_dpp v105, v105, v105 row_ror:2 row_mask:0xf bank_mask:0xf
	v_add_f32_dpp v106, v106, v106 row_ror:2 row_mask:0xf bank_mask:0xf
	v_add_f32_dpp v107, v107, v107 row_ror:2 row_mask:0xf bank_mask:0xf
	v_add_f32_dpp v104, v104, v104 row_ror:1 row_mask:0xf bank_mask:0xf
	v_add_f32_dpp v105, v105, v105 row_ror:1 row_mask:0xf bank_mask:0xf
	v_add_f32_dpp v106, v106, v106 row_ror:1 row_mask:0xf bank_mask:0xf
	v_add_f32_dpp v107, v107, v107 row_ror:1 row_mask:0xf bank_mask:0xf
	s_nop 1
	ds_write_b32 v113, v104 offset:704
	ds_write_b32 v113, v105 offset:720
	ds_write_b32 v113, v106 offset:736
	ds_write_b32 v113, v107 offset:752
	s_waitcnt lgkmcnt(0)
	ds_read_b32 v19, v13 offset:256
	ds_read_b32 v18, v13 offset:512
	s_waitcnt lgkmcnt(0)
	v_mul_f32_e32 v22, 0x3e000000, v19
	v_mul_f32_e32 v23, 0x3e000000, v18
	v_mul_f32_e32 v21, v1, v2
	v_max_f32_e32 v22, v22, v23
	s_lshl_b64 s[0:1], s[18:19], 10
	s_or_b32 s0, s0, s51
	s_movk_i32 s19, 0xfe00
	s_nop 0
	v_add_f32_dpp v21, v21, v21 quad_perm:[1,0,3,2] row_mask:0xf bank_mask:0xf
	v_max_f32_dpp v22, v22, v22 quad_perm:[1,0,3,2] row_mask:0xf bank_mask:0xf
	s_nop 0
	v_add_f32_dpp v21, v21, v21 quad_perm:[2,3,0,1] row_mask:0xf bank_mask:0xf
	v_max_f32_dpp v22, v22, v22 quad_perm:[2,3,0,1] row_mask:0xf bank_mask:0xf
	s_nop 0
	v_add_f32_dpp v21, v21, v21 row_half_mirror row_mask:0xf bank_mask:0xf
	v_max_f32_dpp v22, v22, v22 row_half_mirror row_mask:0xf bank_mask:0xf
	s_nop 0
	v_add_f32_dpp v21, v21, v21 row_mirror row_mask:0xf bank_mask:0xf
	v_max_f32_dpp v22, v22, v22 row_mirror row_mask:0xf bank_mask:0xf
	v_mov_b32_e32 v23, v21
	v_mov_b32_e32 v2, v22
	s_nop 1
	v_permlane16_swap_b32_e32 v21, v23
	v_permlane16_swap_b32_e32 v22, v2
	v_add_f32_e32 v21, v21, v23
	v_max_f32_e32 v22, v22, v2
	v_mov_b32_e32 v23, v21
	v_mov_b32_e32 v2, v22
	s_nop 1
	v_permlane32_swap_b32_e32 v21, v23
	v_permlane32_swap_b32_e32 v22, v2
	v_add_f32_e32 v21, v21, v23
	v_max_f32_e32 v22, v22, v2
	s_waitcnt vmcnt(0)
	v_max_f32_e32 v36, v20, v20
	v_mul_f32_e32 v2, 0x3e000000, v21
	v_max_f32_e32 v2, v2, v36
	v_max_f32_e32 v22, v22, v2
	v_fma_f32 v2, v19, s43, -v22
	v_mul_f32_e32 v2, 0x3fb8aa3b, v2
	v_exp_f32_e32 v19, v2
	v_fma_f32 v2, v18, s43, -v22
	v_mul_f32_e32 v2, 0x3fb8aa3b, v2
	v_exp_f32_e32 v18, v2
	v_fma_f32 v21, v21, s43, -v22
	v_mul_f32_e32 v21, 0x3fb8aa3b, v21
	v_add_f32_e32 v2, v19, v18
	ds_write2st64_b32 v13, v19, v18 offset0:1 offset1:2
	s_waitcnt lgkmcnt(0)
	v_lshl_add_u64 v[18:19], v[8:9], 0, s[0:1]
	v_add_f32_dpp v2, v2, v2 quad_perm:[1,0,3,2] row_mask:0xf bank_mask:0xf
	s_nop 1
	v_add_f32_dpp v2, v2, v2 quad_perm:[2,3,0,1] row_mask:0xf bank_mask:0xf
	s_nop 1
	v_add_f32_dpp v2, v2, v2 row_half_mirror row_mask:0xf bank_mask:0xf
	s_nop 1
	v_add_f32_dpp v36, v2, v2 row_mirror row_mask:0xf bank_mask:0xf
	v_lshlrev_b32_e32 v2, 16, v35
	v_exp_f32_e32 v23, v21
	v_mov_b32_e32 v37, v36
	s_nop 1
	v_permlane16_swap_b32_e32 v36, v37
	v_add_f32_e32 v35, v36, v37
	v_mov_b32_e32 v36, v35
	s_nop 1
	v_permlane32_swap_b32_e32 v35, v36
	v_mul_f32_e32 v21, v23, v2
